# lru tile columns rotated by 15 so WGs that also run a sample-attention item get 8 lru rounds instead of 9
# baseline (speedup 1.0000x reference)
; #define LAS __attribute__((address_space(3)))
; __device__ __forceinline__ int mk_tid(int wv) { int t = wv * 64 + (int)__builtin_amdgcn_mbcnt_hi(~0u, __builtin_amdgcn_mbcnt_lo(~0u, 0u)); asm volatile("" : "+v"(t)); return t; }
; __device__ __forceinline__ unsigned xb_ld(unsigned* p)              { return __hip_atomic_load(p, __ATOMIC_RELAXED, __HIP_MEMORY_SCOPE_AGENT); }
; __device__ __forceinline__ void xcd_barrier_complete(unsigned* bar, unsigned x, unsigned& nloc, unsigned& nx) {
;     const unsigned G = gridDim.x * gridDim.y * gridDim.z;
;     unsigned sum, cnt, mine, sp = 0u;
;     for (;;) {
;         sum = 0u; cnt = 0u; mine = 0u;
; #pragma unroll
;         for (unsigned j = 0; j < 16; ++j) { const unsigned c = xb_ld(&bar[XB_XCNT(j)]); sum += c; cnt += (c > 0u) ? 1u : 0u; mine = (j == x) ? c : mine; }
;         if (sum == G) break;
;         __builtin_amdgcn_s_sleep(1);
;         if ((++sp & 255u) == 0u) { if (xb_ld(&bar[XB_TMO])) break; if (sp > XB_SPIN_CAP) { atomicAdd(&bar[XB_TMO], 1u); break; } }
;     }
;     nloc = mine > 0u ? mine : 1u; nx = cnt > 0u ? cnt : 1u;
; }
; __global__ void __launch_bounds__(512, 2) fwd_mega(Params P) {
;     ...
;     unsigned char* ws = P.ws;
;     const int G = gridDim.x, bx = blockIdx.x;
;     const int wv = __builtin_amdgcn_readfirstlane((int)(threadIdx.x >> 6));
;     bf16* XB = (bf16*)(ws + WS_XB); float* X = (float*)(ws + WS_X);
;     bf16* Qb = (bf16*)((unsigned char*)P.out + OB_Q); bf16* ATT = (bf16*)((unsigned char*)P.out + OB_ATT);
;     bf16 *KB = (bf16*)(ws + WS_KB), *VT = (bf16*)(ws + WS_VT), *XR = (bf16*)(ws + WS_XR), *GG = (bf16*)(ws + WS_GG), *SA = (bf16*)(ws + WS_SA), *SL = (bf16*)(ws + WS_SL), *H = (bf16*)(ws + WS_H);
;     if (threadIdx.x < 4) ((volatile LAS unsigned*)(lds + LDS_ST))[threadIdx.x] = 0u;
;     __syncthreads();
;     const XcdBarrier xbar = xcd_barrier_post((unsigned*)(ws + WS_BAR), (volatile LAS unsigned*)(lds + LDS_ST), mk_tid(wv));
.LBB0_174:
	v_writelane_b32 v253, s36, 15
	s_nop 1
	v_writelane_b32 v253, s37, 16
	v_writelane_b32 v253, s34, 17
	s_nop 1
	v_writelane_b32 v253, s35, 18
	s_or_b64 exec, exec, s[0:1]
	v_readlane_b32 s8, v252, 1
	v_readlane_b32 s12, v252, 5
	v_readlane_b32 s13, v252, 6
	s_add_u32 s20, s12, 0xcb00000
	s_addc_u32 s21, s13, 0
	s_add_u32 s96, s12, 0x8800000
	v_readlane_b32 s10, v252, 3
	s_addc_u32 s97, s13, 0
	v_readlane_b32 s11, v252, 4
	s_add_u32 s86, s10, 0x10c0000
	s_addc_u32 s87, s11, 0
	s_add_u32 s0, s12, 0xec80000
	s_addc_u32 s1, s13, 0
	v_readlane_b32 s14, v252, 7
	v_writelane_b32 v254, s0, 0
	v_readlane_b32 s15, v252, 8
	v_add_u32_e32 v0, 64, v44
	v_writelane_b32 v254, s1, 1
	s_add_u32 s0, s12, 0xf0b0000
	s_addc_u32 s1, s13, 0
	v_writelane_b32 v254, s0, 2
	v_xor_b32_e32 v1, 1, v42
	v_cmp_lt_i32_e32 vcc, v1, v0
	v_writelane_b32 v254, s1, 3
	s_add_u32 s0, s12, 0xf4e0000
	s_addc_u32 s1, s13, 0
	s_add_u32 s78, s12, 0x11660000
	s_addc_u32 s79, s13, 0
	s_add_u32 s80, s12, 0x137e0000
	s_addc_u32 s81, s13, 0
	s_add_u32 s84, s12, 0x15960000
	s_addc_u32 s85, s13, 0
	v_writelane_b32 v254, s0, 4
	s_add_u32 s2, s10, 0x8680000
	s_addc_u32 s3, s11, 0
	v_writelane_b32 v254, s1, 5
	v_writelane_b32 v254, s2, 6
	s_mul_i32 s0, s15, s14
	s_mul_i32 s0, s0, s54
	v_writelane_b32 v254, s3, 7
	s_add_u32 s2, s10, 0x4600000
	s_addc_u32 s3, s11, 0
	v_writelane_b32 v254, s2, 8
	v_readlane_b32 s48, v252, 41
	v_readlane_b32 s56, v252, 49
	v_writelane_b32 v254, s3, 9
	s_add_u32 s2, s10, 0x4680000
	s_addc_u32 s3, s11, 0
	v_writelane_b32 v254, s2, 10
	v_readlane_b32 s57, v252, 50
	v_xor_b32_e32 v2, 2, v42
	v_writelane_b32 v254, s3, 11
	s_add_u32 s2, s10, 0x4200000
	s_addc_u32 s3, s11, 0
	v_writelane_b32 v254, s2, 12
	v_cndmask_b32_e32 v1, v42, v1, vcc
	v_cmp_lt_i32_e32 vcc, v2, v0
	v_writelane_b32 v254, s3, 13
	s_add_u32 s2, s10, 0x6680000
	s_addc_u32 s3, s11, 0
	v_writelane_b32 v254, s2, 14
	v_xor_b32_e32 v3, 4, v42
	v_cndmask_b32_e32 v2, v42, v2, vcc
	v_writelane_b32 v254, s3, 15
	s_add_u32 s2, s10, 0x4400000
	s_addc_u32 s3, s11, 0
	v_writelane_b32 v254, s2, 16
	v_cmp_lt_i32_e32 vcc, v3, v0
	v_xor_b32_e32 v4, 8, v42
	v_writelane_b32 v254, s3, 17
	v_writelane_b32 v254, s0, 18
	s_add_u32 s0, s12, 0x17ae0200
	s_addc_u32 s1, s13, 0
	v_writelane_b32 v254, s0, 19
	v_cndmask_b32_e32 v3, v42, v3, vcc
	v_cmp_lt_i32_e32 vcc, v4, v0
	v_writelane_b32 v254, s1, 20
	s_add_u32 s0, s12, 0x17ae0400
	s_addc_u32 s1, s13, 0
	v_writelane_b32 v254, s0, 21
	v_xor_b32_e32 v5, 16, v42
	v_cndmask_b32_e32 v4, v42, v4, vcc
	v_writelane_b32 v254, s1, 22
	s_add_u32 s0, s12, 0x17ae0500
	s_addc_u32 s1, s13, 0
	v_writelane_b32 v254, s0, 23
	v_cmp_lt_i32_e32 vcc, v5, v0
	v_readlane_b32 s52, v252, 45
	v_writelane_b32 v254, s1, 24
	s_add_u32 s0, s12, 0x17ae0600
	s_addc_u32 s1, s13, 0
	v_writelane_b32 v254, s0, 25
	v_cndmask_b32_e32 v5, v42, v5, vcc
	v_cmp_lt_i32_e32 vcc, v43, v0
	v_writelane_b32 v254, s1, 26
	s_add_u32 s0, s12, 0x17ae0700
	s_addc_u32 s1, s13, 0
	v_writelane_b32 v254, s0, 27
	v_cndmask_b32_e32 v0, v42, v43, vcc
	v_readlane_b32 s53, v252, 46
	v_writelane_b32 v254, s1, 28
	s_add_u32 s0, s12, 0x17ae0800
	s_addc_u32 s1, s13, 0
	v_writelane_b32 v254, s0, 29
	s_mov_b32 s69, 0
	v_lshlrev_b32_e32 v217, 2, v1
	v_writelane_b32 v254, s1, 30
	s_add_u32 s0, s12, 0x17ae0900
	s_addc_u32 s1, s13, 0
	v_writelane_b32 v254, s0, 31
	v_lshlrev_b32_e32 v218, 2, v2
	v_lshlrev_b32_e32 v219, 2, v3
	v_writelane_b32 v254, s1, 32
	s_add_u32 s0, s12, 0x17ae0a00
	s_addc_u32 s1, s13, 0
	v_writelane_b32 v254, s0, 33
	v_lshlrev_b32_e32 v220, 2, v4
	v_lshlrev_b32_e32 v221, 2, v5
	v_writelane_b32 v254, s1, 34
	s_add_u32 s0, s12, 0x17ae0b00
	s_addc_u32 s1, s13, 0
	v_writelane_b32 v254, s0, 35
	v_lshlrev_b32_e32 v222, 2, v0
	v_readlane_b32 s54, v252, 47
	v_writelane_b32 v254, s1, 36
	s_add_u32 s0, s12, 0x17ae0c00
	s_addc_u32 s1, s13, 0
	v_writelane_b32 v254, s0, 37
	v_readlane_b32 s55, v252, 48
	v_readlane_b32 s58, v252, 51
	v_writelane_b32 v254, s1, 38
	s_add_u32 s0, s12, 0x17ae0d00
	s_addc_u32 s1, s13, 0
	v_writelane_b32 v254, s0, 39
	v_readlane_b32 s59, v252, 52
	v_readlane_b32 s62, v252, 55
	v_writelane_b32 v254, s1, 40
	s_add_u32 s0, s12, 0x17ae0e00
	s_addc_u32 s1, s13, 0
	v_writelane_b32 v254, s0, 41
	v_readlane_b32 s63, v252, 56
	v_mov_b32_e32 v81, 0
	v_writelane_b32 v254, s1, 42
	s_add_u32 s0, s12, 0x17ae0f00
	s_addc_u32 s1, s13, 0
	v_writelane_b32 v254, s0, 43
	v_mov_b32_e32 v223, 0x26008
	v_mov_b32_e32 v225, 0x20000
	v_writelane_b32 v254, s1, 44
	s_add_u32 s0, s12, 0x17ae1000
	s_addc_u32 s1, s13, 0
	v_writelane_b32 v254, s0, 45
	v_mov_b32_e32 v232, 0x20580
	v_mov_b32_e32 v233, 0xf149f2ca
	v_writelane_b32 v254, s1, 46
	s_add_u32 s0, s12, 0x17ae1100
	s_addc_u32 s1, s13, 0
	v_writelane_b32 v254, s0, 47
	v_mov_b64_e32 v[230:231], 0x100
	s_mov_b32 s71, 0xfe03f81
	v_writelane_b32 v254, s1, 48
	s_add_u32 s0, s12, 0x17ae1200
	s_addc_u32 s1, s13, 0
	v_writelane_b32 v254, s0, 49
	s_movk_i32 s73, 0x810
	s_movk_i32 s52, 0x7f
	v_writelane_b32 v254, s1, 50
	s_add_u32 s0, s12, 0x17ae1300
	s_addc_u32 s1, s13, 0
	v_writelane_b32 v254, s0, 51
	s_cmp_eq_u32 s33, 15
	s_movk_i32 s83, 0x104
	v_writelane_b32 v254, s1, 52
	s_cselect_b64 s[0:1], -1, 0
	v_writelane_b32 v254, s0, 53
	s_cmp_eq_u32 s33, 14
	s_movk_i32 s53, 0x7c
	v_writelane_b32 v254, s1, 54
	s_cselect_b64 s[0:1], -1, 0
	v_writelane_b32 v254, s0, 55
; template <int MODE> __device__ __forceinline__ void lru_phase(const Params& P, LAS unsigned char* lds, int l, int tid_in) {
;     ...
;     const int nb = blockIdx.x & 7, tstride = gridDim.x >> 3;
;     const int c8 = tid & 15, r0 = tid >> 4, c0 = nb * 128 + c8 * 8;
;     for (int e = tid; e < 640; e += 512) { const int i = e >> 7, cc = e & 127; cwl[e] = i < 4 ? P.in[I_CW][(size_t)(l * 4 + 3 - i) * 1024 + nb * 128 + cc] : P.in[I_CB][l * 1024 + nb * 128 + cc]; }
;     const int rb = wid & 1, cb = wid >> 1, l32 = lane & 31, h = lane >> 5;
;     bf16x8 br[8], bi[8];
;     { const bf16* LW = (const bf16*)(P.ws + WS_LW + l * SZ_LW) + (size_t)(nb * 256 + cb * 32 + l32) * 128 + h * 8;
; #pragma unroll
;       for (int kk = 0; kk < 8; ++kk) { br[kk] = *(const bf16x8*)(LW + kk * 16); bi[kk] = *(const bf16x8*)(LW + 128 * 128 + kk * 16); } }
;     const int cgate = cb * 32 + l32;
;     const float ba = P.in[I_BA][l * 1024 + nb * 128 + cgate], bx = P.in[I_BX][l * 1024 + nb * 128 + cgate];
;     const float sp = log1pf(expf(-P.in[I_LAM][l * 1024 + nb * 128 + cgate]));
;     const float L2E = 1.4426950408889634f, nba = -L2E * ba, nbx = -L2E * bx, ca = -8.f * sp * L2E;
;     const int cs = tid & 127, q = tid >> 7, cgs = nb * 128 + cs;
;     float* AGG = (float*)(P.ws + WS_AGG) + (size_t)l * AGG_LAYER;
;     bf16* GG = (bf16*)(P.ws + WS_GG);
;     u32x4 xr[2][4], gwp[2];
;     float pqa[3] = {1.f, 1.f, 1.f}, pqb[3] = {0.f, 0.f, 0.f};
;     int tile = blockIdx.x >> 3, prev = -1, par = 0;
	s_cmp_eq_u32 s33, 13
	s_mov_b32 s35, 0xefa18f08
	v_writelane_b32 v254, s1, 56
	s_cselect_b64 s[0:1], -1, 0
	v_writelane_b32 v254, s0, 57
	s_cmp_eq_u32 s33, 12
	s_mov_b32 s34, 0x3fd744fd
	v_writelane_b32 v254, s1, 58
	s_cselect_b64 s[0:1], -1, 0
	v_writelane_b32 v254, s0, 59
	s_cmp_eq_u32 s33, 11
	v_readlane_b32 s9, v252, 2
	v_writelane_b32 v254, s1, 60
	s_cselect_b64 s[0:1], -1, 0
	v_writelane_b32 v254, s0, 61
	s_cmp_eq_u32 s33, 10
	v_readlane_b32 s49, v252, 42
	v_writelane_b32 v254, s1, 62
	s_cselect_b64 s[0:1], -1, 0
	v_writelane_b32 v254, s0, 63
	s_cmp_eq_u32 s33, 9
	v_readlane_b32 s50, v252, 43
	v_writelane_b32 v255, s1, 0
	s_cselect_b64 s[0:1], -1, 0
	v_writelane_b32 v255, s0, 1
	s_cmp_eq_u32 s33, 8
	v_readlane_b32 s51, v252, 44
	v_writelane_b32 v255, s1, 2
	s_cselect_b64 s[0:1], -1, 0
	v_writelane_b32 v255, s0, 3
	s_cmp_eq_u32 s33, 7
	v_readlane_b32 s60, v252, 53
	v_writelane_b32 v255, s1, 4
	s_cselect_b64 s[0:1], -1, 0
	v_writelane_b32 v255, s0, 5
	s_cmp_eq_u32 s33, 6
	v_readlane_b32 s61, v252, 54
	v_writelane_b32 v255, s1, 6
	s_cselect_b64 s[0:1], -1, 0
	v_writelane_b32 v255, s0, 7
	s_cmp_eq_u32 s33, 5
	s_nop 0
	v_writelane_b32 v255, s1, 8
	s_cselect_b64 s[0:1], -1, 0
	v_writelane_b32 v255, s0, 9
	s_cmp_eq_u32 s33, 4
	s_nop 0
	v_writelane_b32 v255, s1, 10
	s_cselect_b64 s[0:1], -1, 0
	v_writelane_b32 v255, s0, 11
	s_cmp_eq_u32 s33, 3
	s_nop 0
	v_writelane_b32 v255, s1, 12
	s_cselect_b64 s[0:1], -1, 0
	v_writelane_b32 v255, s0, 13
	s_cmp_eq_u32 s33, 2
	s_nop 0
	v_writelane_b32 v255, s1, 14
	s_cselect_b64 s[0:1], -1, 0
	v_writelane_b32 v255, s0, 15
	s_cmp_eq_u32 s33, 1
	s_nop 0
	v_writelane_b32 v255, s1, 16
	s_cselect_b64 s[0:1], -1, 0
	v_writelane_b32 v255, s0, 17
	s_cmp_eq_u32 s33, 0
	s_nop 0
	v_writelane_b32 v255, s1, 18
	s_cselect_b64 s[0:1], -1, 0
	v_writelane_b32 v255, s0, 19
	s_nop 1
	v_writelane_b32 v255, s1, 20
	s_lshl_b32 s0, s33, 8
	s_add_u32 s0, s6, s0
	s_addc_u32 s1, s7, 0
	s_add_u32 s2, s0, 0x1400
	s_addc_u32 s3, s1, 0
	v_writelane_b32 v255, s2, 21
	s_add_u32 s0, s0, 0x2400
	s_addc_u32 s1, s1, 0
	v_writelane_b32 v255, s3, 22
	v_writelane_b32 v255, s0, 23
	v_readlane_b32 s2, v252, 0
	s_mov_b32 s33, 0x10000
	v_writelane_b32 v255, s1, 24
	s_add_u32 s0, s12, 0x17ae3400
	s_addc_u32 s1, s13, 0
	v_writelane_b32 v255, s0, 25
	s_mov_b64 s[6:7], 0x80
	s_nop 0
	v_writelane_b32 v255, s1, 26
	s_add_u32 s0, s12, 0x17ae3500
	s_addc_u32 s1, s13, 0
	v_writelane_b32 v255, s0, 27
	s_nop 1
	v_writelane_b32 v255, s1, 28
	s_not_b32 s0, s2
	s_add_i32 s0, s14, s0
	s_cmpk_lt_i32 s0, 0x304
	v_writelane_b32 v255, s0, 29
	s_cselect_b64 s[0:1], -1, 0
	v_writelane_b32 v255, s0, 30
	s_nop 1
	v_writelane_b32 v255, s1, 31
	s_and_b32 s0, s2, 7
	s_lshr_b32 s1, s14, 3
	v_writelane_b32 v255, s1, 32
	s_lshl_b32 s1, s0, 7
	v_writelane_b32 v255, s1, 33
	s_lshl_b32 s1, s0, 9
	s_add_u32 s4, s56, s1
	s_addc_u32 s5, s57, 0
	v_writelane_b32 v255, s4, 34
	s_add_u32 s1, s12, 0x7c00000
	s_movk_i32 s56, 0x1ff
	v_writelane_b32 v255, s5, 35
	v_writelane_b32 v255, s1, 36
	s_addc_u32 s1, s13, 0
	v_writelane_b32 v255, s1, 37
	s_lshl_b32 s0, s0, 8
	v_writelane_b32 v255, s0, 38
	s_lshr_b32 s0, s2, 3
	s_add_i32 s0, s0, 15
	s_and_b32 s0, s0, 31
	s_cmpk_gt_u32 s2, 0x84f
	s_cselect_b64 s[4:5], -1, 0
	v_writelane_b32 v255, s4, 39
	s_movk_i32 s57, 0x210
	s_nop 0
	v_writelane_b32 v255, s5, 40
	v_writelane_b32 v255, s0, 41
	s_lshl_b32 s0, s0, 6
	s_cmpk_gt_u32 s2, 0x80f
	v_writelane_b32 v255, s0, 42
	s_cselect_b64 s[0:1], -1, 0
	v_writelane_b32 v255, s0, 43
	s_mov_b32 s4, s69
	s_nop 0
	v_writelane_b32 v255, s1, 44
	s_add_u32 s0, s10, 0x4660000
	s_addc_u32 s1, s11, 0
	v_writelane_b32 v255, s0, 45
	s_nop 1
	v_writelane_b32 v255, s1, 46
	s_add_u32 s0, s10, 0x8c80000
	s_addc_u32 s1, s11, 0
	v_writelane_b32 v255, s0, 47
	s_mov_b32 s10, 0x18000
	s_mov_b32 s11, 0x8000
	v_writelane_b32 v255, s1, 48
	s_add_u32 s0, s12, 0x2600000
	v_writelane_b32 v255, s0, 49
	s_addc_u32 s0, s13, 0
	s_cmpk_lt_i32 s2, 0xa0
	v_writelane_b32 v255, s0, 50
	s_cselect_b64 s[0:1], -1, 0
	v_writelane_b32 v255, s0, 51
	s_nop 1
	v_writelane_b32 v255, s1, 52
	s_add_u32 s0, s12, 0x2a00000
	v_writelane_b32 v255, s0, 53
	s_addc_u32 s0, s13, 0
	v_writelane_b32 v255, s0, 54
	s_add_u32 s0, s12, 0x3200000
	v_writelane_b32 v255, s0, 55
	s_addc_u32 s0, s13, 0
	v_writelane_b32 v255, s0, 56
	s_add_u32 s0, s12, 0x3a00000
	v_writelane_b32 v255, s0, 57
	s_addc_u32 s0, s13, 0
	v_writelane_b32 v255, s0, 58
	s_add_u32 s0, s12, 0x6600000
	v_writelane_b32 v255, s0, 59
	s_addc_u32 s0, s13, 0
	v_writelane_b32 v255, s0, 60
	s_add_i32 s0, 0, 0x26000
	v_writelane_b32 v255, s0, 61
	s_add_i32 s0, 0, 0x26004
	v_writelane_b32 v255, s0, 62
	s_add_i32 s0, 0, 0x11210
	v_writelane_b32 v255, s0, 63
	s_add_i32 s0, 0, 0x10a10
	v_writelane_b32 v253, s0, 0
	s_add_i32 s0, 0, 0x24400
	v_writelane_b32 v253, s0, 1
	s_add_i32 s0, 0, 0x24c00
	v_writelane_b32 v253, s0, 2
	s_add_i32 s0, 0, 0x24e00
	v_writelane_b32 v253, s0, 3
	s_add_i32 s0, 0, 0x25600
	v_writelane_b32 v253, s0, 4
	v_writelane_b32 v253, s78, 5
	s_nop 1
	v_writelane_b32 v253, s79, 6
	v_writelane_b32 v253, s80, 7
	s_nop 1
	v_writelane_b32 v253, s81, 8
	v_writelane_b32 v253, s84, 9
	s_nop 1
	v_writelane_b32 v253, s85, 10
	v_writelane_b32 v253, s86, 11
	s_nop 1
	v_writelane_b32 v253, s87, 12
	v_writelane_b32 v253, s20, 13
	s_nop 1
	v_writelane_b32 v253, s21, 14
	s_branch .LBB0_177
